# gdn part-A items (64-row): conv-weight and gate loads issued right after the item's first barrier, ahead of the raw-input loads (two fewer exposed global round trips per item)
# speedup vs baseline: 1.0185x; 1.0009x over previous
.LBB0_828:
	s_and_b64 vcc, exec, s[0:1]
	s_cbranch_vccz .LBB0_865
	v_mov_b32_e32 v80, v230
	s_lshl_b32 s6, s88, 2
	s_and_b32 s8, s6, 0x7c0
	s_movk_i32 s0, 0xc90
	v_mul_hi_i32 v1, v80, s21
	s_and_b32 s5, s31, 15
	v_readfirstlane_b32 s4, v80
	s_and_b32 s7, s6, 0x7ffff800
	s_add_i32 s8, s8, -3
	v_cmp_gt_i32_e32 vcc, s0, v80
	v_mov_b32_e32 v0, 0
	v_lshrrev_b32_e32 v28, 31, v1
	v_ashrrev_i32_e32 v29, 3, v1
	v_mov_b32_e32 v4, 0
	v_mov_b32_e32 v5, 0
	v_mov_b32_e32 v6, 0
	v_mov_b32_e32 v7, 0
	s_barrier
	v_cmp_gt_i32_e64 s[98:99], s24, v80
	v_readlane_b32 s100, v253, 41
	v_readlane_b32 s101, v253, 42
	v_bfe_u32 v222, v80, 5, 2
	v_lshlrev_b32_e32 v223, 2, v80
	v_ashrrev_i32_e32 v224, 7, v80
	v_and_b32_e32 v223, 0x7c, v223
	v_mul_u32_u24_e32 v222, 0x1800, v222
	v_lshlrev_b32_e32 v222, 2, v222
	v_lshl_add_u32 v222, v224, 13, v222
	v_lshl_add_u32 v222, v223, 2, v222
	v_lshl_add_u32 v222, s5, 9, v222
	s_and_saveexec_b64 s[98:99], s[98:99]
	global_load_dwordx4 v[244:247], v222, s[100:101]
	s_mov_b64 exec, s[98:99]
	v_cmp_gt_i32_e64 s[98:99], 64, v80
	v_readlane_b32 s100, v254, 48
	v_readlane_b32 s101, v254, 49
	v_mov_b32_e32 v226, s5
	v_lshlrev_b32_e32 v226, 2, v226
	v_mov_b32_e32 v225, 0x7fffffc0
	v_and_b32_e32 v225, s6, v225
	v_add_u32_e32 v225, v225, v80
	v_lshlrev_b32_e32 v225, 7, v225
	v_lshl_add_u32 v225, s5, 2, v225
	s_and_saveexec_b64 s[98:99], s[98:99]
	global_load_dword v248, v226, s[100:101]
	s_mov_b64 exec, s[98:99]
	v_readlane_b32 s100, v255, 8
	v_readlane_b32 s101, v255, 9
	v_cmp_gt_i32_e64 s[98:99], 64, v80
	s_nop 4
	s_and_saveexec_b64 s[98:99], s[98:99]
	global_load_dword v249, v225, s[100:101]
	global_load_dword v250, v225, s[100:101] offset:64
	s_mov_b64 exec, s[98:99]
	s_mov_b32 s98, 0
	s_mov_b32 s99, 0
	s_and_saveexec_b64 s[36:37], vcc
	s_cbranch_execz .LBB0_833
	v_add3_u32 v2, v29, v28, s8
	v_cmp_lt_i32_e64 s[0:1], -1, v2
	v_mov_b32_e32 v7, 0
	v_mov_b32_e32 v6, 0
	v_mov_b32_e32 v5, 0
	v_mov_b32_e32 v4, 0
	s_and_saveexec_b64 s[38:39], s[0:1]
	s_cbranch_execz .LBB0_832
	v_lshrrev_b32_e32 v1, 3, v1
	v_add_u32_e32 v1, v1, v28
	v_mul_lo_u32 v1, v1, 48
	v_sub_u32_e32 v1, v80, v1
	v_and_b32_e32 v3, 0x1fffff0, v1
	v_lshlrev_b32_e32 v1, 3, v1
	v_or_b32_e32 v3, s5, v3
	v_and_b32_e32 v1, 0x78, v1
	v_lshl_or_b32 v4, v3, 7, v1
	v_add_u32_e32 v1, s7, v2
	v_mov_b64_e32 v[2:3], s[92:93]
	v_mad_u64_u32 v[2:3], s[0:1], v1, s22, v[2:3]
	v_ashrrev_i32_e32 v5, 31, v4
	v_lshl_add_u64 v[2:3], v[4:5], 1, v[2:3]
	global_load_dwordx4 v[4:7], v[2:3], off

.LBB0_864:
	s_waitcnt vmcnt(0)
	v_bfe_u32 v5, v80, 5, 2
	v_lshlrev_b32_e32 v0, 2, v80
	v_ashrrev_i32_e32 v4, 7, v80
	v_and_b32_e32 v6, 0x7c, v0
	v_mul_u32_u24_e32 v0, 0x1800, v5
	v_readlane_b32 s36, v253, 37
	v_lshlrev_b32_e32 v104, 2, v0
	v_readlane_b32 s40, v253, 41
	v_readlane_b32 s41, v253, 42
	v_lshlrev_b32_e32 v2, 11, v4
	v_ashrrev_i32_e32 v3, 31, v2
	v_lshl_add_u64 v[0:1], s[40:41], 0, v[104:105]
	v_lshl_add_u64 v[0:1], v[2:3], 2, v[0:1]
	s_lshl_b32 s14, s5, 9
	v_lshl_add_u64 v[0:1], v[0:1], 0, s[14:15]
	v_lshlrev_b32_e32 v104, 2, v6
	v_lshl_add_u64 v[0:1], v[0:1], 0, v[104:105]
	v_lshlrev_b32_e32 v4, 9, v4
	v_lshlrev_b32_e32 v5, 7, v5
	v_or3_b32 v4, v5, v4, v6
	v_lshl_add_u32 v4, v4, 2, 0
	v_add_u32_e32 v4, 0x1ca00, v4
	v_readlane_b32 s37, v253, 38
	v_readlane_b32 s38, v253, 39
	v_readlane_b32 s39, v253, 40
	v_readlane_b32 s42, v253, 43
	v_readlane_b32 s43, v253, 44
	v_readlane_b32 s44, v253, 45
	v_readlane_b32 s45, v253, 46
	v_readlane_b32 s46, v253, 47
	v_readlane_b32 s47, v253, 48
	v_readlane_b32 s48, v253, 49
	v_readlane_b32 s49, v253, 50
	v_readlane_b32 s50, v253, 51
	v_readlane_b32 s51, v253, 52
	s_waitcnt vmcnt(0)
	ds_write_b128 v4, v[244:247]
	s_or_b64 exec, exec, s[0:1]
	v_cmp_gt_i32_e32 vcc, 64, v80
	s_and_saveexec_b64 s[0:1], vcc
	s_cbranch_execz .LBB0_900
	s_branch .LBB0_897

.LBB0_897:
	s_and_b32 s6, s6, 0x7fffffc0
	s_waitcnt vmcnt(0)
	v_add_u32_e32 v0, s6, v80
	v_ashrrev_i32_e32 v1, 31, v0
	v_readlane_b32 s6, v255, 8
	v_lshlrev_b64 v[0:1], 7, v[0:1]
	v_readlane_b32 s7, v255, 9
	s_lshl_b32 s14, s5, 2
	v_readlane_b32 s36, v254, 46
	v_lshl_add_u64 v[0:1], s[6:7], 0, v[0:1]
	v_lshl_add_u64 v[0:1], v[0:1], 0, s[14:15]
	v_mov_b32_e32 v2, s14
	v_readlane_b32 s38, v254, 48
	v_readlane_b32 s39, v254, 49
	s_nop 4
	v_mov_b32_e32 v2, v248
	s_nop 0
	v_mov_b32_e32 v3, v249
	s_nop 0
	v_mov_b32_e32 v0, v250
	s_mov_b32 s5, 0x41a00000
	v_readlane_b32 s37, v254, 47
	v_readlane_b32 s40, v254, 50
	v_readlane_b32 s41, v254, 51
	v_readlane_b32 s42, v254, 52
	v_readlane_b32 s43, v254, 53
	v_readlane_b32 s44, v254, 54
	v_readlane_b32 s45, v254, 55
	v_readlane_b32 s46, v254, 56
	v_readlane_b32 s47, v254, 57
	v_readlane_b32 s48, v254, 58
	v_readlane_b32 s49, v254, 59
	v_readlane_b32 s50, v254, 60
	v_readlane_b32 s51, v254, 61
	s_waitcnt vmcnt(1)
	v_add_f32_e32 v1, v3, v2
	v_cmp_nlt_f32_e32 vcc, s5, v1
	s_and_saveexec_b64 s[36:37], vcc
	s_cbranch_execz .LBB0_899
	v_mul_f32_e32 v1, 0x3fb8aa3b, v1
	v_exp_f32_e32 v1, v1
	s_mov_b32 s5, 0x3f2aaaab
	v_add_f32_e32 v4, 1.0, v1
	v_frexp_mant_f32_e32 v6, v4
	v_cvt_f64_f32_e32 v[2:3], v4
	v_frexp_exp_i32_f64_e32 v2, v[2:3]
	v_cmp_gt_f32_e32 vcc, s5, v6
	v_add_f32_e32 v5, -1.0, v4
	v_sub_f32_e32 v7, v5, v4
	v_subbrev_co_u32_e32 v10, vcc, 0, v2, vcc
	v_sub_u32_e32 v2, 0, v10
	v_sub_f32_e32 v5, v1, v5
	v_add_f32_e32 v7, 1.0, v7
	v_ldexp_f32 v3, v4, v2
	v_add_f32_e32 v5, v5, v7
	v_add_f32_e32 v4, -1.0, v3
	v_add_f32_e32 v6, 1.0, v3
	v_ldexp_f32 v2, v5, v2
	v_add_f32_e32 v5, 1.0, v4
	v_add_f32_e32 v7, -1.0, v6
	v_sub_f32_e32 v5, v3, v5
	v_sub_f32_e32 v3, v3, v7
	v_add_f32_e32 v5, v2, v5
	v_add_f32_e32 v2, v2, v3
	v_add_f32_e32 v11, v6, v2
	v_rcp_f32_e32 v13, v11
	v_sub_f32_e32 v3, v11, v6
	v_sub_f32_e32 v12, v2, v3
	v_add_f32_e32 v3, v4, v5
	v_mul_f32_e32 v15, v3, v13
	v_sub_f32_e32 v2, v3, v4
	v_mul_f32_e32 v4, v11, v15
	v_fma_f32 v6, v15, v11, -v4
	v_fmac_f32_e32 v6, v15, v12
	v_sub_f32_e32 v14, v5, v2
	v_add_f32_e32 v2, v4, v6
	v_sub_f32_e32 v5, v3, v2
	v_pk_add_f32 v[8:9], v[2:3], v[4:5] neg_lo:[0,1] neg_hi:[0,1]
	v_mov_b32_e32 v7, v2
	v_pk_add_f32 v[2:3], v[8:9], v[6:7] neg_lo:[0,1] neg_hi:[0,1]
	s_mov_b32 s5, 0x3f317218
	v_add_f32_e32 v3, v14, v3
	v_add_f32_e32 v2, v2, v3
	v_add_f32_e32 v3, v5, v2
	v_mul_f32_e32 v14, v13, v3
	v_mul_f32_e32 v4, v11, v14
	v_fma_f32 v6, v14, v11, -v4
	v_fmac_f32_e32 v6, v14, v12
	v_sub_f32_e32 v5, v5, v3
	v_add_f32_e32 v11, v2, v5
	v_add_f32_e32 v2, v4, v6
	v_sub_f32_e32 v5, v3, v2
	v_pk_add_f32 v[8:9], v[2:3], v[4:5] neg_lo:[0,1] neg_hi:[0,1]
	v_mov_b32_e32 v7, v2
	v_pk_add_f32 v[2:3], v[8:9], v[6:7] neg_lo:[0,1] neg_hi:[0,1]
	s_nop 0
	v_add_f32_e32 v3, v11, v3
	v_add_f32_e32 v2, v2, v3
	v_add_f32_e32 v3, v15, v14
	v_add_f32_e32 v2, v5, v2
	v_sub_f32_e32 v4, v3, v15
	v_mul_f32_e32 v2, v13, v2
	v_sub_f32_e32 v4, v14, v4
	v_add_f32_e32 v4, v4, v2
	v_add_f32_e32 v6, v3, v4
	v_mul_f32_e32 v7, v6, v6
	v_fmamk_f32 v2, v7, 0x3e9b6dac, v127
	v_fmaak_f32 v107, v7, v2, 0x3f2aaada
	v_cvt_f32_i32_e32 v2, v10
	v_sub_f32_e32 v3, v6, v3
	v_sub_f32_e32 v3, v4, v3
	v_ldexp_f32 v8, v3, 1
	v_mul_f32_e32 v3, v6, v7
	v_ldexp_f32 v5, v6, 1
	v_pk_mul_f32 v[6:7], v[2:3], v[106:107]
	s_nop 0
	v_fma_f32 v4, v2, s5, -v6
	v_fmac_f32_e32 v4, 0xb102e308, v2
	v_pk_add_f32 v[2:3], v[6:7], v[4:5]
	s_mov_b32 s5, 0x7f800000
	v_sub_f32_e32 v5, v3, v5
	v_sub_f32_e32 v5, v7, v5
	v_add_f32_e32 v9, v8, v5
	v_mov_b32_e32 v8, v6
	v_pk_add_f32 v[6:7], v[2:3], v[6:7] neg_lo:[0,1] neg_hi:[0,1]
	v_pk_add_f32 v[10:11], v[2:3], v[8:9]
	v_mov_b32_e32 v5, v2
	v_mov_b32_e32 v7, v11
	v_pk_add_f32 v[12:13], v[4:5], v[6:7] neg_lo:[0,1] neg_hi:[0,1]
	v_pk_add_f32 v[4:5], v[4:5], v[6:7]
	v_mov_b32_e32 v8, v9
	v_pk_add_f32 v[6:7], v[4:5], v[2:3] op_sel:[1,0] op_sel_hi:[0,1] neg_lo:[0,1] neg_hi:[0,1]
	v_pk_add_f32 v[14:15], v[10:11], v[6:7] op_sel_hi:[1,0] neg_lo:[0,1] neg_hi:[0,1]
	v_mov_b32_e32 v10, v11
	v_mov_b32_e32 v11, v5
	v_pk_mov_b32 v[6:7], v[2:3], v[6:7] op_sel:[1,0]
	v_mov_b32_e32 v9, v2
	v_pk_add_f32 v[6:7], v[10:11], v[6:7] neg_lo:[0,1] neg_hi:[0,1]
	v_mov_b32_e32 v14, v12
	v_pk_add_f32 v[2:3], v[8:9], v[6:7] neg_lo:[0,1] neg_hi:[0,1]
	v_mov_b32_e32 v13, v5
	v_pk_add_f32 v[6:7], v[14:15], v[2:3]
	v_cmp_neq_f32_e32 vcc, s5, v1
	v_pk_add_f32 v[8:9], v[6:7], v[6:7] op_sel:[0,1] op_sel_hi:[1,0]
	s_mov_b32 s5, 0x33800000
	v_pk_add_f32 v[4:5], v[4:5], v[8:9] op_sel:[1,0] op_sel_hi:[0,1]
	v_mov_b32_e32 v7, v4
	v_pk_add_f32 v[10:11], v[6:7], v[12:13] neg_lo:[0,1] neg_hi:[0,1]
	v_mov_b32_e32 v3, v8
	v_sub_f32_e32 v5, v6, v10
	v_pk_add_f32 v[2:3], v[2:3], v[10:11] neg_lo:[0,1] neg_hi:[0,1]
	v_sub_f32_e32 v5, v12, v5
	v_add_f32_e32 v2, v2, v5
	v_add_f32_e32 v2, v2, v3
	v_add_f32_e32 v2, v4, v2
	v_cndmask_b32_e32 v2, v130, v2, vcc
	v_cmp_ngt_f32_e32 vcc, -1.0, v1
	s_nop 1
	v_cndmask_b32_e32 v2, v131, v2, vcc
	v_cmp_neq_f32_e32 vcc, -1.0, v1
	s_nop 1
	v_cndmask_b32_e32 v2, v132, v2, vcc
	v_cmp_lt_f32_e64 vcc, |v1|, s5
	s_nop 1
	v_cndmask_b32_e32 v1, v2, v1, vcc
